# LayerNorm phase: gate/gamma/beta/scale/shift vector loads issued together at top of each iteration instead of one at a time behind vmcnt(0)
# speedup vs baseline: 1.0678x; 1.0053x over previous
.LBB0_2432:
	s_add_i32 s6, s76, s10
	s_cmp_lt_i32 s6, 0x8000
	s_cselect_b32 s24, s6, s10
	s_cmpk_gt_i32 s10, 0x3fff
	s_cselect_b64 s[6:7], -1, 0
	v_cndmask_b32_e64 v2, 0, 1, s[6:7]
	s_and_b64 s[6:7], s[6:7], exec
	v_readfirstlane_b32 s7, v2
	s_cselect_b32 s6, 0x9000, 0
	s_or_b32 s7, s34, s7
	s_mul_i32 s48, s7, 0x2400
	s_lshl_b64 s[8:9], s[48:49], 2
	s_add_u32 s20, s35, s8
	s_addc_u32 s21, s40, s9
	s_ashr_i32 s25, s24, 31
	s_cmpk_gt_i32 s24, 0x3fff
	s_cselect_b64 s[26:27], -1, 0
	s_and_b64 s[8:9], s[26:27], exec
	s_cselect_b32 s48, 0x9000, 0
	s_add_u32 s22, s20, 0x1000
	s_addc_u32 s23, s21, 0
	s_lshl_b64 s[8:9], s[24:25], 12
	v_lshl_add_u64 v[4:5], v[28:29], 0, s[8:9]
	s_lshl_b64 s[8:9], s[24:25], 11
	v_lshl_add_u64 v[6:7], s[14:15], 0, v[42:43]
	v_lshl_add_u64 v[56:57], v[30:31], 0, s[8:9]
	s_mov_b32 s8, 0x19900000
	s_mov_b32 s7, s49
	v_add_co_u32_e32 v58, vcc, s8, v6
	v_lshl_add_u64 v[2:3], s[18:19], 0, v[10:11]
	s_nop 0
	v_addc_co_u32_e32 v59, vcc, 0, v7, vcc
	v_lshl_add_u64 v[70:71], v[38:39], 0, s[6:7]
	s_cmpk_gt_i32 s24, 0x3fff
	s_cselect_b32 s41, 1, 0
	s_or_b32 s41, s34, s41
	s_mul_i32 s62, s41, 0x2400
	s_mov_b32 s63, 0
	s_lshl_b64 s[62:63], s[62:63], 2
	s_add_u32 s50, s35, s62
	s_addc_u32 s51, s40, s63
	s_add_u32 s54, s50, 0x1000
	s_addc_u32 s55, s51, 0
	v_lshlrev_b32_e32 v234, 2, v26
	v_lshl_add_u64 v[236:237], v[38:39], 0, s[48:49]
	global_load_dwordx4 v[190:193], v[70:71], off
	global_load_dwordx4 v[194:197], v[70:71], off offset:1024
	global_load_dwordx4 v[198:201], v[70:71], off offset:2048
	global_load_dwordx4 v[214:217], v[70:71], off offset:3072
	global_load_dwordx4 v[218:221], v[236:237], off
	global_load_dwordx4 v[222:225], v[236:237], off offset:1024
	global_load_dwordx4 v[226:229], v[236:237], off offset:2048
	global_load_dwordx4 v[230:233], v[236:237], off offset:3072
	global_load_dwordx4 v[84:87], v[34:35], off
	global_load_dwordx4 v[88:91], v[34:35], off offset:1024
	global_load_dwordx4 v[92:95], v[34:35], off offset:2048
	global_load_dwordx4 v[96:99], v[34:35], off offset:3072
	global_load_dwordx4 v[100:103], v[36:37], off
	global_load_dwordx4 v[104:107], v[36:37], off offset:1024
	global_load_dwordx4 v[108:111], v[36:37], off offset:2048
	global_load_dwordx4 v[112:115], v[36:37], off offset:3072
	global_load_dwordx4 v[116:119], v234, s[22:23]
	global_load_dwordx4 v[120:123], v27, s[22:23]
	global_load_dwordx4 v[124:127], v74, s[22:23]
	global_load_dwordx4 v[128:131], v75, s[22:23]
	global_load_dwordx4 v[132:135], v234, s[20:21]
	global_load_dwordx4 v[136:139], v234, s[20:21] offset:1024
	global_load_dwordx4 v[140:143], v234, s[20:21] offset:2048
	global_load_dwordx4 v[144:147], v234, s[20:21] offset:3072
	global_load_dwordx4 v[148:151], v234, s[54:55]
	global_load_dwordx4 v[152:155], v27, s[54:55]
	global_load_dwordx4 v[156:159], v74, s[54:55]
	global_load_dwordx4 v[160:163], v75, s[54:55]
	global_load_dwordx4 v[164:167], v234, s[50:51]
	global_load_dwordx4 v[168:171], v234, s[50:51] offset:1024
	global_load_dwordx4 v[182:185], v234, s[50:51] offset:2048
	global_load_dwordx4 v[186:189], v234, s[50:51] offset:3072
	global_load_dwordx4 v[44:47], v[2:3], off nt
	global_load_dwordx4 v[48:51], v[4:5], off nt
	global_load_dwordx2 v[62:63], v[58:59], off nt
	global_load_dwordx2 v[72:73], v[56:57], off nt
	global_load_dwordx4 v[76:79], v[2:3], off offset:1024 nt
	global_load_dwordx4 v[20:23], v[4:5], off offset:1024 nt
	global_load_dwordx2 v[80:81], v[58:59], off offset:512 nt
	global_load_dwordx2 v[54:55], v[56:57], off offset:512 nt
	global_load_dwordx4 v[16:19], v[2:3], off offset:2048 nt
	global_load_dwordx4 v[12:15], v[4:5], off offset:2048 nt
	global_load_dwordx2 v[52:53], v[58:59], off offset:1024 nt
	global_load_dwordx2 v[60:61], v[56:57], off offset:1024 nt
	global_load_dwordx4 v[6:9], v[2:3], off offset:3072 nt
	s_nop 0
	global_load_dwordx4 v[2:5], v[4:5], off offset:3072 nt
	s_nop 0
	global_load_dwordx2 v[68:69], v[58:59], off offset:1536 nt
	global_load_dwordx2 v[64:65], v[56:57], off offset:1536 nt
	v_mov_b32_e32 v25, v24
	s_waitcnt vmcnt(16)
	v_mov_b64_e32 v[56:57], v[190:191]
	v_mov_b64_e32 v[58:59], v[192:193]
	s_mov_b32 s6, 0x3a800000
	s_waitcnt vmcnt(13)
	v_and_b32_e32 v67, 0xffff0000, v63
	v_lshlrev_b32_e32 v66, 16, v63
	v_and_b32_e32 v63, 0xffff0000, v62
	v_lshlrev_b32_e32 v62, 16, v62
	s_waitcnt vmcnt(0)
	v_pk_add_f32 v[58:59], v[58:59], 1.0 op_sel_hi:[1,0]
	v_pk_add_f32 v[56:57], v[56:57], 1.0 op_sel_hi:[1,0]
	v_pk_mul_f32 v[58:59], v[24:25], v[58:59]
	v_pk_mul_f32 v[56:57], v[32:33], v[56:57]
	s_nop 0
	v_pk_mul_f32 v[62:63], v[56:57], v[62:63]
	v_pk_mul_f32 v[56:57], v[58:59], v[66:67]
	v_lshl_add_u64 v[66:67], v[38:39], 0, s[48:49]
	v_pk_fma_f32 v[56:57], v[46:47], s[72:73], v[56:57] op_sel_hi:[1,0,1]
	v_pk_fma_f32 v[58:59], v[44:45], s[72:73], v[62:63] op_sel_hi:[1,0,1]
	v_mov_b64_e32 v[44:45], v[218:219]
	v_mov_b64_e32 v[46:47], v[220:221]
	v_and_b32_e32 v63, 0xffff0000, v73
	v_lshlrev_b32_e32 v62, 16, v73
	v_and_b32_e32 v73, 0xffff0000, v72
	v_lshlrev_b32_e32 v72, 16, v72
	s_waitcnt vmcnt(0)
	v_pk_add_f32 v[46:47], v[46:47], 1.0 op_sel_hi:[1,0]
	v_pk_add_f32 v[44:45], v[44:45], 1.0 op_sel_hi:[1,0]
	v_pk_mul_f32 v[46:47], v[24:25], v[46:47]
	v_pk_mul_f32 v[44:45], v[32:33], v[44:45]
	s_nop 0
	v_pk_mul_f32 v[72:73], v[44:45], v[72:73]
	v_pk_mul_f32 v[44:45], v[46:47], v[62:63]
	v_pk_fma_f32 v[46:47], v[48:49], s[72:73], v[72:73] op_sel_hi:[1,0,1]
	v_pk_fma_f32 v[44:45], v[50:51], s[72:73], v[44:45] op_sel_hi:[1,0,1]
	v_mov_b64_e32 v[48:49], v[194:195]
	v_mov_b64_e32 v[50:51], v[196:197]
	v_and_b32_e32 v63, 0xffff0000, v81
	v_lshlrev_b32_e32 v62, 16, v81
	v_and_b32_e32 v73, 0xffff0000, v80
	v_lshlrev_b32_e32 v72, 16, v80
	s_waitcnt vmcnt(0)
	v_pk_add_f32 v[50:51], v[50:51], 1.0 op_sel_hi:[1,0]
	v_pk_add_f32 v[48:49], v[48:49], 1.0 op_sel_hi:[1,0]
	v_pk_mul_f32 v[50:51], v[24:25], v[50:51]
	v_pk_mul_f32 v[48:49], v[32:33], v[48:49]
	s_nop 0
	v_pk_mul_f32 v[72:73], v[48:49], v[72:73]
	v_pk_mul_f32 v[48:49], v[50:51], v[62:63]
	v_pk_fma_f32 v[50:51], v[76:77], s[72:73], v[72:73] op_sel_hi:[1,0,1]
	v_pk_fma_f32 v[48:49], v[78:79], s[72:73], v[48:49] op_sel_hi:[1,0,1]
	v_mov_b64_e32 v[76:77], v[222:223]
	v_mov_b64_e32 v[78:79], v[224:225]
	v_and_b32_e32 v63, 0xffff0000, v55
	v_lshlrev_b32_e32 v62, 16, v55
	v_and_b32_e32 v55, 0xffff0000, v54
	v_lshlrev_b32_e32 v54, 16, v54
	s_waitcnt vmcnt(0)
	v_pk_add_f32 v[76:77], v[76:77], 1.0 op_sel_hi:[1,0]
	s_nop 0
	v_pk_mul_f32 v[76:77], v[32:33], v[76:77]
	v_pk_add_f32 v[72:73], v[78:79], 1.0 op_sel_hi:[1,0]
	v_pk_mul_f32 v[54:55], v[76:77], v[54:55]
	v_mov_b64_e32 v[76:77], v[198:199]
	v_mov_b64_e32 v[78:79], v[200:201]
	v_pk_mul_f32 v[72:73], v[24:25], v[72:73]
	s_nop 0
	v_pk_mul_f32 v[62:63], v[72:73], v[62:63]
	s_waitcnt vmcnt(0)
	v_pk_add_f32 v[72:73], v[76:77], 1.0 op_sel_hi:[1,0]
	v_pk_fma_f32 v[22:23], v[22:23], s[72:73], v[62:63] op_sel_hi:[1,0,1]
	v_pk_fma_f32 v[62:63], v[20:21], s[72:73], v[54:55] op_sel_hi:[1,0,1]
	v_pk_add_f32 v[54:55], v[78:79], 1.0 op_sel_hi:[1,0]
	v_and_b32_e32 v21, 0xffff0000, v53
	v_lshlrev_b32_e32 v20, 16, v53
	v_and_b32_e32 v53, 0xffff0000, v52
	v_lshlrev_b32_e32 v52, 16, v52
	v_pk_mul_f32 v[54:55], v[24:25], v[54:55]
	v_pk_mul_f32 v[72:73], v[32:33], v[72:73]
	v_pk_mul_f32 v[20:21], v[54:55], v[20:21]
	v_pk_mul_f32 v[72:73], v[72:73], v[52:53]
	v_pk_fma_f32 v[52:53], v[18:19], s[72:73], v[20:21] op_sel_hi:[1,0,1]
	v_pk_fma_f32 v[54:55], v[16:17], s[72:73], v[72:73] op_sel_hi:[1,0,1]
	v_mov_b64_e32 v[16:17], v[226:227]
	v_mov_b64_e32 v[18:19], v[228:229]
	v_and_b32_e32 v21, 0xffff0000, v61
	v_lshlrev_b32_e32 v20, 16, v61
	v_and_b32_e32 v61, 0xffff0000, v60
	v_lshlrev_b32_e32 v60, 16, v60
	s_waitcnt vmcnt(0)
	v_pk_add_f32 v[18:19], v[18:19], 1.0 op_sel_hi:[1,0]
	v_pk_add_f32 v[16:17], v[16:17], 1.0 op_sel_hi:[1,0]
	v_pk_mul_f32 v[18:19], v[24:25], v[18:19]
	v_pk_mul_f32 v[16:17], v[32:33], v[16:17]
	s_nop 0
	v_pk_mul_f32 v[60:61], v[16:17], v[60:61]
	v_pk_mul_f32 v[16:17], v[18:19], v[20:21]
	v_pk_fma_f32 v[60:61], v[12:13], s[72:73], v[60:61] op_sel_hi:[1,0,1]
	v_pk_fma_f32 v[16:17], v[14:15], s[72:73], v[16:17] op_sel_hi:[1,0,1]
	v_mov_b64_e32 v[12:13], v[214:215]
	v_mov_b64_e32 v[14:15], v[216:217]
	v_and_b32_e32 v19, 0xffff0000, v69
	v_lshlrev_b32_e32 v18, 16, v69
	v_and_b32_e32 v21, 0xffff0000, v68
	v_lshlrev_b32_e32 v20, 16, v68
	v_lshl_add_u64 v[70:71], s[12:13], 0, v[10:11]
	s_waitcnt vmcnt(0)
	v_pk_add_f32 v[14:15], v[14:15], 1.0 op_sel_hi:[1,0]
	v_pk_add_f32 v[12:13], v[12:13], 1.0 op_sel_hi:[1,0]
	v_pk_mul_f32 v[14:15], v[24:25], v[14:15]
	v_pk_mul_f32 v[12:13], v[32:33], v[12:13]
	v_pk_mul_f32 v[14:15], v[14:15], v[18:19]
	v_pk_mul_f32 v[12:13], v[12:13], v[20:21]
	v_pk_fma_f32 v[18:19], v[8:9], s[72:73], v[14:15] op_sel_hi:[1,0,1]
	v_pk_fma_f32 v[20:21], v[6:7], s[72:73], v[12:13] op_sel_hi:[1,0,1]
	v_mov_b64_e32 v[6:7], v[230:231]
	v_mov_b64_e32 v[8:9], v[232:233]
	v_and_b32_e32 v15, 0xffff0000, v64
	v_lshlrev_b32_e32 v14, 16, v64
	v_and_b32_e32 v13, 0xffff0000, v65
	v_lshlrev_b32_e32 v12, 16, v65
	s_waitcnt vmcnt(0)
	v_pk_add_f32 v[6:7], v[6:7], 1.0 op_sel_hi:[1,0]
	v_pk_add_f32 v[8:9], v[8:9], 1.0 op_sel_hi:[1,0]
	v_pk_mul_f32 v[6:7], v[32:33], v[6:7]
	v_pk_mul_f32 v[8:9], v[24:25], v[8:9]
	v_pk_mul_f32 v[6:7], v[6:7], v[14:15]
	v_pk_mul_f32 v[8:9], v[8:9], v[12:13]
	v_pk_fma_f32 v[66:67], v[2:3], s[72:73], v[6:7] op_sel_hi:[1,0,1]
	v_add_f32_e32 v2, v58, v59
	v_add_f32_e32 v3, v56, v57
	v_pk_fma_f32 v[64:65], v[4:5], s[72:73], v[8:9] op_sel_hi:[1,0,1]
	v_add_f32_e32 v2, v2, v3
	v_add_f32_e32 v3, v50, v51
	v_add_f32_e32 v4, v48, v49
	v_add_f32_e32 v2, 0, v2
	v_add_f32_e32 v3, v3, v4
	v_add_f32_e32 v2, v2, v3
	v_add_f32_e32 v3, v54, v55
	v_add_f32_e32 v4, v52, v53
	v_add_f32_e32 v3, v3, v4
	v_add_f32_e32 v2, v2, v3
	v_add_f32_e32 v3, v20, v21
	v_add_f32_e32 v4, v18, v19
	v_add_f32_e32 v3, v3, v4
	v_add_f32_e32 v2, v2, v3
	v_add_f32_e32 v3, v46, v47
	v_add_f32_e32 v4, v44, v45
	v_add_f32_e32 v3, v3, v4
	v_add_f32_e32 v4, v62, v63
	v_add_f32_e32 v5, v22, v23
	v_add_f32_e32 v3, 0, v3
	v_add_f32_e32 v4, v4, v5
	v_add_f32_e32 v3, v3, v4
	v_add_f32_e32 v4, v60, v61
	v_add_f32_e32 v5, v16, v17
	v_add_f32_dpp v2, v2, v2 quad_perm:[1,0,3,2] row_mask:0xf bank_mask:0xf bound_ctrl:1
	v_add_f32_e32 v4, v4, v5
	v_add_f32_e32 v3, v3, v4
	v_add_f32_dpp v2, v2, v2 quad_perm:[2,3,0,1] row_mask:0xf bank_mask:0xf bound_ctrl:1
	v_add_f32_e32 v4, v66, v67
	v_add_f32_e32 v5, v64, v65
	v_add_f32_dpp v2, v2, v2 row_half_mirror row_mask:0xf bank_mask:0xf bound_ctrl:1
	v_add_f32_e32 v4, v4, v5
	v_add_f32_e32 v4, v3, v4
	v_add_f32_dpp v2, v2, v2 row_mirror row_mask:0xf bank_mask:0xf bound_ctrl:1
	v_mov_b32_e32 v3, v2
	s_nop 1
	v_permlane16_swap_b32 v2, v3
	s_nop 1
	v_cndmask_b32_e64 v25, 0, 1, s[4:5]
	v_add_f32_e32 v2, v2, v3
	v_mov_b32_e32 v3, v2
	s_nop 1
	v_permlane32_swap_b32 v2, v3
	s_nop 1
	s_nop 0
	v_add_f32_e32 v2, v2, v3
	v_fmac_f32_e32 v57, 0xba800000, v2
	v_fmac_f32_e32 v59, 0xba800000, v2
	v_fmamk_f32 v56, v2, 0xba800000, v56
	v_fmamk_f32 v58, v2, 0xba800000, v58
	v_mul_f32_e32 v3, v59, v59
	v_mul_f32_e32 v5, v57, v57
	v_fmac_f32_e32 v3, v58, v58
	v_fmac_f32_e32 v5, v56, v56
	v_fmamk_f32 v49, v2, 0xba800000, v49
	v_fmamk_f32 v51, v2, 0xba800000, v51
	v_add_f32_e32 v3, v3, v5
	v_fmac_f32_e32 v48, 0xba800000, v2
	v_fmac_f32_e32 v50, 0xba800000, v2
	v_mul_f32_e32 v5, v51, v51
	v_mul_f32_e32 v6, v49, v49
	v_fmac_f32_e32 v5, v50, v50
	v_fmac_f32_e32 v6, v48, v48
	v_add_f32_e32 v5, v5, v6
	v_fmamk_f32 v53, v2, 0xba800000, v53
	v_fmamk_f32 v55, v2, 0xba800000, v55
	v_add_f32_e32 v3, v3, v5
	v_fmac_f32_e32 v52, 0xba800000, v2
	v_fmac_f32_e32 v54, 0xba800000, v2
	v_mul_f32_e32 v5, v55, v55
	v_mul_f32_e32 v6, v53, v53
	v_fmac_f32_e32 v5, v54, v54
	v_fmac_f32_e32 v6, v52, v52
	v_add_f32_e32 v5, v5, v6
	v_fmamk_f32 v19, v2, 0xba800000, v19
	v_fmamk_f32 v21, v2, 0xba800000, v21
	v_add_f32_e32 v3, v5, v3
	v_fmac_f32_e32 v18, 0xba800000, v2
	v_fmac_f32_e32 v20, 0xba800000, v2
	v_mul_f32_e32 v2, v21, v21
	v_mul_f32_e32 v5, v19, v19
	v_fmac_f32_e32 v2, v20, v20
	v_fmac_f32_e32 v5, v18, v18
	v_add_f32_e32 v2, v2, v5
	v_add_f32_e32 v2, v2, v3
	s_nop 1
	v_add_f32_dpp v2, v2, v2 quad_perm:[1,0,3,2] row_mask:0xf bank_mask:0xf bound_ctrl:1
	s_nop 1
	v_add_f32_dpp v2, v2, v2 quad_perm:[2,3,0,1] row_mask:0xf bank_mask:0xf bound_ctrl:1
	s_nop 1
	v_add_f32_dpp v2, v2, v2 row_half_mirror row_mask:0xf bank_mask:0xf bound_ctrl:1
	s_nop 1
	v_add_f32_dpp v2, v2, v2 row_mirror row_mask:0xf bank_mask:0xf bound_ctrl:1
	v_mov_b32_e32 v3, v2
	s_nop 1
	v_permlane16_swap_b32 v2, v3
	s_nop 1
	s_nop 0
	v_add_f32_e32 v3, v2, v3
	v_add_f32_dpp v2, v4, v4 quad_perm:[1,0,3,2] row_mask:0xf bank_mask:0xf bound_ctrl:1
	v_mov_b32_e32 v5, v3
	s_nop 1
	v_permlane32_swap_b32 v3, v5
	s_nop 1
	s_nop 0
	v_add_f32_dpp v2, v2, v2 quad_perm:[2,3,0,1] row_mask:0xf bank_mask:0xf bound_ctrl:1
	s_nop 1
	v_add_f32_dpp v2, v2, v2 row_half_mirror row_mask:0xf bank_mask:0xf bound_ctrl:1
	s_nop 1
	v_add_f32_dpp v2, v2, v2 row_mirror row_mask:0xf bank_mask:0xf bound_ctrl:1
	v_mov_b32_e32 v4, v2
	s_nop 1
	v_permlane16_swap_b32 v2, v4
	s_nop 1
	s_nop 0
	v_add_f32_e32 v2, v2, v4
	v_mov_b32_e32 v4, v2
	s_nop 1
	v_permlane32_swap_b32 v2, v4
	s_nop 1
	s_nop 0
	v_add_f32_e32 v2, v2, v4
	v_fmamk_f32 v45, v2, 0xba800000, v45
	v_fmamk_f32 v47, v2, 0xba800000, v47
	v_fmac_f32_e32 v44, 0xba800000, v2
	v_fmac_f32_e32 v46, 0xba800000, v2
	v_mul_f32_e32 v4, v47, v47
	v_mul_f32_e32 v6, v45, v45
	v_fmac_f32_e32 v4, v46, v46
	v_fmac_f32_e32 v6, v44, v44
	v_fmamk_f32 v23, v2, 0xba800000, v23
	v_fmamk_f32 v63, v2, 0xba800000, v63
	v_add_f32_e32 v4, v4, v6
	v_fmac_f32_e32 v22, 0xba800000, v2
	v_fmac_f32_e32 v62, 0xba800000, v2
	v_mul_f32_e32 v6, v63, v63
	v_mul_f32_e32 v7, v23, v23
	v_fmac_f32_e32 v6, v62, v62
	v_fmac_f32_e32 v7, v22, v22
	v_add_f32_e32 v6, v6, v7
	v_fmamk_f32 v17, v2, 0xba800000, v17
	v_fmamk_f32 v61, v2, 0xba800000, v61
	v_add_f32_e32 v4, v4, v6
	v_fmac_f32_e32 v16, 0xba800000, v2
	v_fmac_f32_e32 v60, 0xba800000, v2
	v_mul_f32_e32 v6, v61, v61
	v_mul_f32_e32 v7, v17, v17
	v_fmac_f32_e32 v6, v60, v60
	v_fmac_f32_e32 v7, v16, v16
	v_add_f32_e32 v6, v6, v7
	v_fmamk_f32 v65, v2, 0xba800000, v65
	v_fmamk_f32 v67, v2, 0xba800000, v67
	v_add_f32_e32 v4, v6, v4
	v_fmac_f32_e32 v64, 0xba800000, v2
	v_fmac_f32_e32 v66, 0xba800000, v2
	v_mul_f32_e32 v2, v67, v67
	v_mul_f32_e32 v6, v65, v65
	v_fmac_f32_e32 v2, v66, v66
	v_fmac_f32_e32 v6, v64, v64
	v_add_f32_e32 v2, v2, v6
	v_add_f32_e32 v2, v2, v4
	s_nop 1
	v_add_f32_dpp v2, v2, v2 quad_perm:[1,0,3,2] row_mask:0xf bank_mask:0xf bound_ctrl:1
	s_nop 1
	v_add_f32_dpp v2, v2, v2 quad_perm:[2,3,0,1] row_mask:0xf bank_mask:0xf bound_ctrl:1
	s_nop 1
	v_add_f32_dpp v2, v2, v2 row_half_mirror row_mask:0xf bank_mask:0xf bound_ctrl:1
	s_nop 1
	v_add_f32_dpp v2, v2, v2 row_mirror row_mask:0xf bank_mask:0xf bound_ctrl:1
	v_mov_b32_e32 v4, v2
	s_nop 1
	v_permlane16_swap_b32 v2, v4
	s_nop 1
	s_nop 0
	v_add_f32_e32 v2, v2, v4
	v_mov_b32_e32 v4, v2
	s_nop 1
	v_permlane32_swap_b32 v2, v4
	s_nop 1
	s_nop 0
	v_pk_add_f32 v[2:3], v[2:3], v[4:5]
	s_nop 0
	v_pk_fma_f32 v[72:73], v[2:3], s[6:7], v[174:175] op_sel_hi:[1,0,0]
	v_cmp_ne_u32_e64 s[6:7], 1, v25
	v_mul_f32_e32 v2, 0x4b800000, v73
	v_cmp_gt_f32_e32 vcc, s52, v73
	v_cmp_gt_f32_e64 s[8:9], s52, v72
	v_lshlrev_b32_e32 v25, 2, v26
	v_cndmask_b32_e32 v2, v73, v2, vcc
	v_rsq_f32_e32 v2, v2
	s_nop 0
	v_mul_f32_e32 v3, 0x45800000, v2
	v_cndmask_b32_e32 v68, v2, v3, vcc
	s_nop 1
	v_mov_b64_e32 v[2:3], v[84:85]
	v_mov_b64_e32 v[4:5], v[86:87]
	s_nop 1
	v_mov_b64_e32 v[6:7], v[100:101]
	v_mov_b64_e32 v[8:9], v[102:103]
	v_pk_mul_f32 v[12:13], v[58:59], v[68:69] op_sel_hi:[1,0]
	v_pk_mul_f32 v[14:15], v[56:57], v[68:69] op_sel_hi:[1,0]
	s_andn2_b64 vcc, exec, s[4:5]
	v_lshl_add_u64 v[56:57], s[16:17], 0, v[42:43]
	v_pk_fma_f32 v[14:15], v[4:5], v[14:15], v[8:9]
	v_pk_fma_f32 v[12:13], v[2:3], v[12:13], v[6:7]
	global_store_dwordx4 v[70:71], v[12:15], off nt
	s_cbranch_vccnz .LBB0_2434
	s_nop 1
	v_mov_b64_e32 v[76:77], v[116:117]
	v_mov_b64_e32 v[78:79], v[118:119]
	s_nop 1
	v_mov_b64_e32 v[80:81], v[132:133]
	v_mov_b64_e32 v[82:83], v[134:135]
	v_pk_add_f32 v[58:59], v[78:79], 1.0 op_sel_hi:[1,0]
	v_pk_add_f32 v[76:77], v[76:77], 1.0 op_sel_hi:[1,0]
	v_pk_fma_f32 v[14:15], v[14:15], v[58:59], v[82:83]
	v_pk_fma_f32 v[12:13], v[12:13], v[76:77], v[80:81]
	s_nop 0
	v_cvt_pk_bf16_f32 v12, v12, v13
	v_cvt_pk_bf16_f32 v13, v14, v15
	v_add_co_u32_e32 v14, vcc, 0x5800000, v56
	s_nop 1
	v_addc_co_u32_e32 v15, vcc, 0, v57, vcc
	global_store_dwordx2 v[14:15], v[12:13], off
.LBB0_2434:
	s_nop 0
	v_cndmask_b32_e64 v12, 0, 1, s[26:27]
	s_lshl_b64 s[46:47], s[24:25], 10
	v_readfirstlane_b32 s11, v12
	v_mul_f32_e32 v12, 0x4b800000, v72
	s_or_b32 s11, s34, s11
	v_cndmask_b32_e64 v12, v72, v12, s[8:9]
	s_mul_i32 s48, s11, 0x2400
	v_rsq_f32_e32 v12, v12
	s_lshl_b64 s[24:25], s[48:49], 2
	s_add_u32 s26, s35, s24
	s_addc_u32 s27, s40, s25
	s_lshl_b64 s[24:25], s[46:47], 1
	s_add_u32 s24, s30, s24
	v_mul_f32_e32 v13, 0x45800000, v12
	s_addc_u32 s25, s31, s25
	v_cndmask_b32_e64 v58, v12, v13, s[8:9]
	s_add_u32 s28, s26, 0x1000
	v_pk_mul_f32 v[12:13], v[46:47], v[58:59] op_sel_hi:[1,0]
	v_pk_mul_f32 v[14:15], v[44:45], v[58:59] op_sel_hi:[1,0]
	s_addc_u32 s29, s27, 0
	v_pk_fma_f32 v[4:5], v[4:5], v[14:15], v[8:9]
	v_pk_fma_f32 v[2:3], v[2:3], v[12:13], v[6:7]
	v_lshl_add_u64 v[44:45], s[46:47], 2, v[40:41]
	s_and_b64 vcc, exec, s[6:7]
	v_lshlrev_b32_e32 v72, 1, v26
	global_store_dwordx4 v[44:45], v[2:5], off nt
	s_cbranch_vccnz .LBB0_2436
	s_nop 1
	v_mov_b64_e32 v[6:7], v[148:149]
	v_mov_b64_e32 v[8:9], v[150:151]
	s_nop 1
	v_mov_b64_e32 v[12:13], v[164:165]
	v_mov_b64_e32 v[14:15], v[166:167]
	v_pk_add_f32 v[6:7], v[6:7], 1.0 op_sel_hi:[1,0]
	v_pk_add_f32 v[8:9], v[8:9], 1.0 op_sel_hi:[1,0]
	v_pk_fma_f32 v[2:3], v[2:3], v[6:7], v[12:13]
	v_pk_fma_f32 v[4:5], v[4:5], v[8:9], v[14:15]
	v_cvt_pk_bf16_f32 v2, v2, v3
	s_nop 0
	v_cvt_pk_bf16_f32 v3, v4, v5
	global_store_dwordx2 v72, v[2:3], s[24:25]
.LBB0_2436:
	s_nop 1
	v_mov_b64_e32 v[2:3], v[88:89]
	v_mov_b64_e32 v[4:5], v[90:91]
	s_nop 0
	s_nop 1
	v_mov_b64_e32 v[6:7], v[104:105]
	v_mov_b64_e32 v[8:9], v[106:107]
	v_mov_b32_e32 v69, v68
	v_mov_b32_e32 v12, v68
	v_mov_b32_e32 v13, v68
	v_mov_b32_e32 v59, v58
	v_pk_mul_f32 v[12:13], v[48:49], v[12:13]
	v_pk_mul_f32 v[46:47], v[50:51], v[68:69]
	s_mov_b64 s[8:9], -1
	s_and_b64 vcc, exec, s[6:7]
	v_pk_fma_f32 v[14:15], v[12:13], v[4:5], v[8:9]
	v_pk_fma_f32 v[12:13], v[46:47], v[2:3], v[6:7]
	v_pk_mul_f32 v[46:47], v[62:63], v[58:59]
	global_store_dwordx4 v[70:71], v[12:15], off offset:1024 nt
	s_cbranch_vccnz .LBB0_2438
	s_nop 1
	v_mov_b64_e32 v[48:49], v[120:121]
	v_mov_b64_e32 v[50:51], v[122:123]
	s_nop 1
	v_mov_b64_e32 v[76:77], v[136:137]
	v_mov_b64_e32 v[78:79], v[138:139]
	s_mov_b32 s8, 0x5800000
	v_pk_add_f32 v[50:51], v[50:51], 1.0 op_sel_hi:[1,0]
	v_pk_add_f32 v[48:49], v[48:49], 1.0 op_sel_hi:[1,0]
	v_pk_fma_f32 v[14:15], v[14:15], v[50:51], v[78:79]
	v_pk_fma_f32 v[12:13], v[12:13], v[48:49], v[76:77]
	s_nop 0
	v_cvt_pk_bf16_f32 v12, v12, v13
	v_cvt_pk_bf16_f32 v13, v14, v15
	v_add_co_u32_e32 v14, vcc, s8, v56
	s_mov_b64 s[8:9], 0
	s_nop 0
	v_addc_co_u32_e32 v15, vcc, 0, v57, vcc
	global_store_dwordx2 v[14:15], v[12:13], off offset:512
	v_mov_b32_e32 v12, v58
	v_mov_b32_e32 v13, v58
	v_pk_mul_f32 v[12:13], v[22:23], v[12:13]
	s_nop 0
	v_pk_fma_f32 v[14:15], v[12:13], v[4:5], v[8:9]
	v_pk_fma_f32 v[12:13], v[46:47], v[2:3], v[6:7]
	global_store_dwordx4 v[44:45], v[12:15], off offset:1024 nt
	s_nop 1
	v_mov_b64_e32 v[48:49], v[152:153]
	v_mov_b64_e32 v[50:51], v[154:155]
	s_nop 1
	v_mov_b64_e32 v[76:77], v[168:169]
	v_mov_b64_e32 v[78:79], v[170:171]
	v_pk_add_f32 v[48:49], v[48:49], 1.0 op_sel_hi:[1,0]
	v_pk_add_f32 v[50:51], v[50:51], 1.0 op_sel_hi:[1,0]
	v_pk_fma_f32 v[12:13], v[12:13], v[48:49], v[76:77]
	v_pk_fma_f32 v[14:15], v[14:15], v[50:51], v[78:79]
	v_cvt_pk_bf16_f32 v12, v12, v13
	s_nop 0
	v_cvt_pk_bf16_f32 v13, v14, v15
	global_store_dwordx2 v72, v[12:13], s[24:25] offset:512

.LBB0_2440:
	s_nop 1
	v_mov_b64_e32 v[2:3], v[92:93]
	v_mov_b64_e32 v[4:5], v[94:95]
	s_nop 0
	s_nop 1
	v_mov_b64_e32 v[6:7], v[108:109]
	v_mov_b64_e32 v[8:9], v[110:111]
	v_mov_b32_e32 v12, v68
	v_mov_b32_e32 v13, v68
	v_pk_mul_f32 v[22:23], v[54:55], v[68:69]
	v_pk_mul_f32 v[12:13], v[52:53], v[12:13]
	s_mov_b64 s[8:9], -1
	s_and_b64 vcc, exec, s[6:7]
	v_pk_fma_f32 v[14:15], v[12:13], v[4:5], v[8:9]
	v_pk_fma_f32 v[12:13], v[22:23], v[2:3], v[6:7]
	v_pk_mul_f32 v[22:23], v[60:61], v[58:59]
	global_store_dwordx4 v[70:71], v[12:15], off offset:2048 nt
	s_cbranch_vccnz .LBB0_2442
	s_nop 1
	v_mov_b64_e32 v[46:47], v[124:125]
	v_mov_b64_e32 v[48:49], v[126:127]
	s_nop 1
	v_mov_b64_e32 v[50:51], v[140:141]
	v_mov_b64_e32 v[52:53], v[142:143]
	s_mov_b32 s8, 0x5800000
	v_pk_add_f32 v[48:49], v[48:49], 1.0 op_sel_hi:[1,0]
	v_pk_add_f32 v[46:47], v[46:47], 1.0 op_sel_hi:[1,0]
	v_pk_fma_f32 v[14:15], v[14:15], v[48:49], v[52:53]
	v_pk_fma_f32 v[12:13], v[12:13], v[46:47], v[50:51]
	s_nop 0
	v_cvt_pk_bf16_f32 v12, v12, v13
	v_cvt_pk_bf16_f32 v13, v14, v15
	v_add_co_u32_e32 v14, vcc, s8, v56
	s_mov_b64 s[8:9], 0
	s_nop 0
	v_addc_co_u32_e32 v15, vcc, 0, v57, vcc
	global_store_dwordx2 v[14:15], v[12:13], off offset:1024
	v_mov_b32_e32 v12, v58
	v_mov_b32_e32 v13, v58
	v_pk_mul_f32 v[12:13], v[16:17], v[12:13]
	s_nop 0
	v_pk_fma_f32 v[14:15], v[12:13], v[4:5], v[8:9]
	v_pk_fma_f32 v[12:13], v[22:23], v[2:3], v[6:7]
	global_store_dwordx4 v[44:45], v[12:15], off offset:2048 nt
	s_nop 1
	v_mov_b64_e32 v[46:47], v[156:157]
	v_mov_b64_e32 v[48:49], v[158:159]
	s_nop 1
	v_mov_b64_e32 v[50:51], v[182:183]
	v_mov_b64_e32 v[52:53], v[184:185]
	v_pk_add_f32 v[46:47], v[46:47], 1.0 op_sel_hi:[1,0]
	v_pk_add_f32 v[48:49], v[48:49], 1.0 op_sel_hi:[1,0]
	v_pk_fma_f32 v[12:13], v[12:13], v[46:47], v[50:51]
	v_pk_fma_f32 v[14:15], v[14:15], v[48:49], v[52:53]
	v_cvt_pk_bf16_f32 v12, v12, v13
	s_nop 0
	v_cvt_pk_bf16_f32 v13, v14, v15
	global_store_dwordx2 v72, v[12:13], s[24:25] offset:1024

.LBB0_2444:
	s_nop 1
	v_mov_b64_e32 v[2:3], v[96:97]
	v_mov_b64_e32 v[4:5], v[98:99]
	s_nop 0
	s_nop 1
	v_mov_b64_e32 v[6:7], v[112:113]
	v_mov_b64_e32 v[8:9], v[114:115]
	v_mov_b32_e32 v12, v68
	v_mov_b32_e32 v13, v68
	v_pk_mul_f32 v[16:17], v[20:21], v[68:69]
	v_pk_mul_f32 v[12:13], v[18:19], v[12:13]
	s_mov_b64 s[8:9], -1
	s_and_b64 vcc, exec, s[6:7]
	v_pk_fma_f32 v[14:15], v[12:13], v[4:5], v[8:9]
	v_pk_fma_f32 v[12:13], v[16:17], v[2:3], v[6:7]
	v_pk_mul_f32 v[16:17], v[66:67], v[58:59]
	global_store_dwordx4 v[70:71], v[12:15], off offset:3072 nt
	s_cbranch_vccnz .LBB0_2446
	s_nop 1
	v_mov_b64_e32 v[18:19], v[128:129]
	v_mov_b64_e32 v[20:21], v[130:131]
	s_nop 1
	v_mov_b64_e32 v[46:47], v[144:145]
	v_mov_b64_e32 v[48:49], v[146:147]
	s_mov_b32 s6, 0x5800000
	v_mov_b32_e32 v59, v58
	s_mov_b64 s[8:9], 0
	v_pk_add_f32 v[20:21], v[20:21], 1.0 op_sel_hi:[1,0]
	v_pk_add_f32 v[18:19], v[18:19], 1.0 op_sel_hi:[1,0]
	v_pk_fma_f32 v[14:15], v[14:15], v[20:21], v[48:49]
	v_pk_fma_f32 v[12:13], v[12:13], v[18:19], v[46:47]
	s_nop 0
	v_cvt_pk_bf16_f32 v12, v12, v13
	v_cvt_pk_bf16_f32 v13, v14, v15
	v_add_co_u32_e32 v14, vcc, s6, v56
	s_nop 1
	v_addc_co_u32_e32 v15, vcc, 0, v57, vcc
	global_store_dwordx2 v[14:15], v[12:13], off offset:1536
	v_pk_mul_f32 v[12:13], v[64:65], v[58:59]
	s_nop 0
	v_pk_fma_f32 v[14:15], v[12:13], v[4:5], v[8:9]
	v_pk_fma_f32 v[12:13], v[16:17], v[2:3], v[6:7]
	global_store_dwordx4 v[44:45], v[12:15], off offset:3072 nt
	s_nop 1
	v_mov_b64_e32 v[18:19], v[160:161]
	v_mov_b64_e32 v[20:21], v[162:163]
	s_nop 1
	v_mov_b64_e32 v[46:47], v[186:187]
	v_mov_b64_e32 v[48:49], v[188:189]
	v_pk_add_f32 v[18:19], v[18:19], 1.0 op_sel_hi:[1,0]
	v_pk_add_f32 v[20:21], v[20:21], 1.0 op_sel_hi:[1,0]
	v_pk_fma_f32 v[12:13], v[12:13], v[18:19], v[46:47]
	v_pk_fma_f32 v[14:15], v[14:15], v[20:21], v[48:49]
	v_cvt_pk_bf16_f32 v12, v12, v13
	s_nop 0
	v_cvt_pk_bf16_f32 v13, v14, v15
	global_store_dwordx2 v72, v[12:13], s[24:25] offset:1536
